# mla_finalize: all per-token loads hoisted into one batch at the top of the token iteration (no load waits behind stores), k-gain loads once per item, V transpose tile staged position-permuted to cut L
# speedup vs baseline: 1.0273x; 1.0087x over previous
; #define LAS __attribute__((address_space(3)))
; DI void mla_finalize(PPtr p, int j, ldsp lds, int tid, int wave, int lane) {
;     const bf16_t* aout = (const bf16_t*)(p->ws + WS_AOUT); const bf16_t* qraw = (const bf16_t*)(p->ws + WS_QRAW); const bf16_t* kvraw = (const bf16_t*)(p->ws + WS_KVRAW);
;     bf16_t* Qb = (bf16_t*)(p->ws + WS_QB); bf16_t* Kb = (bf16_t*)(p->ws + WS_KB); bf16_t* Vt = (bf16_t*)(p->ws + WS_VT);
;     const float* qg = p->mla_q_gain + j * QKH; const float* kg = p->mla_k_gain + j * QKH;
;     constexpr int VTP = 40;
;     const int head = lane >> 2, sub = lane & 3;
;     for (int item = blockIdx.x; item < T / 32; item += gridDim.x) {
;         const int t0 = item * 32, b = t0 >> 12, s0 = t0 & 4095;
;     ...
;         for (int k = 0; k < 8; ++k) { const int id = tid + 512 * k, row = id >> 2, ch = id & 3;
;             const u32x4 w = *(const LAS u32x4*)(lds + (row * VTP + ch * 8) * 2);
;             *(u32x4*)(Vt + ((size_t)b * 1024 + row) * SEQ + s0 + ch * 8) = w; }
.LBB0_781:
	s_movk_i32 s7, 0x800
	s_and_b64 vcc, exec, s[4:5]
	v_readlane_b32 s51, v254, 40
	s_cbranch_vccz .LBB0_923
	v_readlane_b32 s2, v254, 18
	v_readlane_b32 s3, v254, 19
	v_mov_b32_e32 v2, v153
	s_andn2_b64 vcc, exec, s[2:3]
	v_cndmask_b32_e64 v0, 0, 1, s[2:3]
	v_cmp_ne_u32_e64 s[0:1], 1, v0
	v_readfirstlane_b32 s4, v2
	s_cbranch_vccnz .LBB0_791
	v_xor_b32_e32 v0, 1, v204
	v_cmp_lt_i32_e64 s[6:7], v0, v214
	v_readlane_b32 s12, v255, 3
	v_readlane_b32 s13, v255, 4
	v_cndmask_b32_e64 v0, v204, v0, s[6:7]
	v_lshlrev_b32_e32 v39, 2, v0
	v_xor_b32_e32 v0, 2, v204
	v_cmp_lt_i32_e64 s[6:7], v0, v214
	s_load_dwordx2 s[2:3], s[12:13], 0xc8
	v_bfe_u32 v38, v2, 2, 4
	v_cndmask_b32_e64 v0, v204, v0, s[6:7]
	v_lshlrev_b32_e32 v77, 2, v0
	v_xor_b32_e32 v0, 4, v204
	v_cmp_lt_i32_e64 s[6:7], v0, v214
	v_lshlrev_b32_e32 v10, 3, v2
	s_waitcnt lgkmcnt(0)
	s_add_u32 s14, s2, 0xd240000
	v_cndmask_b32_e64 v0, v204, v0, s[6:7]
	s_waitcnt vmcnt(2)
	v_lshlrev_b32_e32 v130, 2, v0
	v_xor_b32_e32 v0, 8, v204
	v_cmp_lt_i32_e64 s[6:7], v0, v214
	s_addc_u32 s15, s3, 0
	s_mov_b64 s[18:19], 0x11a40000
	v_cndmask_b32_e64 v0, v204, v0, s[6:7]
	v_lshlrev_b32_e32 v131, 2, v0
	v_xor_b32_e32 v0, 16, v204
	v_cmp_lt_i32_e64 s[6:7], v0, v214
	s_add_u32 s16, s2, 0x1ba40000
	v_and_b32_e32 v3, 63, v2
	v_cndmask_b32_e64 v0, v204, v0, s[6:7]
	v_lshlrev_b32_e32 v132, 2, v0
	v_and_b32_e32 v0, 15, v2
	v_cvt_f32_ubyte0_e32 v0, v0
	v_mul_f32_e32 v4, 0xbf549a78, v0
	s_mov_b32 s6, 0xc2fc0000
	v_cmp_gt_f32_e64 s[6:7], s6, v4
	v_mov_b32_e32 v4, 0x42800000
	s_addc_u32 s17, s3, 0
	v_cndmask_b32_e64 v4, 0, v4, s[6:7]
	v_fmac_f32_e32 v4, 0xbf549a78, v0
	v_exp_f32_e32 v0, v4
	v_xor_b32_e32 v4, 32, v204
	v_cmp_lt_i32_e64 s[8:9], v4, v214
	s_ashr_i32 s20, s4, 4
	s_and_b32 s21, s20, -4
	v_cndmask_b32_e64 v4, v204, v4, s[8:9]
	v_lshlrev_b32_e32 v133, 2, v4
	v_not_b32_e32 v4, 63
	v_cndmask_b32_e64 v4, 0, v4, s[6:7]
	v_ldexp_f32 v134, v0, v4
	v_and_b32_e32 v0, 64, v204
	v_and_or_b32 v11, v10, 8, v0
	v_lshlrev_b32_e32 v0, 8, v38
	s_load_dwordx4 s[8:11], s[12:13], 0x68
	s_nop 0
	s_load_dwordx2 s[12:13], s[12:13], 0x10
	v_lshl_add_u64 v[6:7], s[2:3], 0, v[0:1]
	v_lshl_add_u64 v[40:41], v[6:7], 0, s[18:19]
	v_mul_u32_u24_e32 v0, 0x60, v38
	v_readlane_b32 s18, v254, 57
	v_lshlrev_b32_e32 v0, 1, v0
	v_readlane_b32 s19, v254, 58
	v_lshl_add_u64 v[6:7], s[2:3], 0, v[0:1]
	v_lshlrev_b32_e32 v0, 4, v3
	v_ashrrev_i32_e32 v12, 2, v2
	s_lshl_b64 s[18:19], s[18:19], 2
	v_and_b32_e32 v5, 3, v2
	v_lshl_add_u64 v[42:43], s[14:15], 0, v[0:1]
	v_and_b32_e32 v10, 24, v10
	v_mul_lo_u32 v0, v12, 40
	s_waitcnt lgkmcnt(0)
	s_add_u32 s8, s8, s18
	v_add_lshl_u32 v15, v0, v10, 1
	s_addc_u32 s9, s9, s19
	v_lshlrev_b32_e32 v0, 5, v5
	v_lshlrev_b32_e32 v8, 4, v5
	v_lshl_add_u64 v[44:45], s[8:9], 0, v[0:1]
	s_add_u32 s8, s10, s18
	v_lshl_or_b32 v13, v38, 6, v8
	s_addc_u32 s9, s11, s19
	v_cmp_gt_u32_e32 vcc, 48, v3
	v_cmp_gt_u32_e64 s[4:5], 32, v3
	v_lshl_add_u64 v[46:47], s[8:9], 0, v[0:1]
	v_mul_u32_u24_e32 v0, 40, v13
	v_ashrrev_i32_e32 v13, 31, v12
	v_add_u32_e32 v3, 0x200, v2
	v_lshlrev_b64 v[48:49], 13, v[12:13]
	v_ashrrev_i32_e32 v12, 2, v3
	v_mul_lo_u32 v3, v12, 40
	v_lshlrev_b32_e32 v4, 3, v5
	v_cmp_gt_u32_e64 s[6:7], 2, v5
	v_add_lshl_u32 v5, v3, v10, 1
	v_ashrrev_i32_e32 v13, 31, v12
	v_add_u32_e32 v3, 0x400, v2
	v_lshlrev_b64 v[50:51], 13, v[12:13]
	v_ashrrev_i32_e32 v12, 2, v3
	v_mul_lo_u32 v3, v12, 40
	v_lshlrev_b32_e32 v135, 2, v11
	v_add_lshl_u32 v11, v3, v10, 1
	v_ashrrev_i32_e32 v13, 31, v12
	v_add_u32_e32 v3, 0x600, v2
	v_lshlrev_b64 v[52:53], 13, v[12:13]
	v_ashrrev_i32_e32 v12, 2, v3
	v_mul_lo_u32 v3, v12, 40
	v_add_lshl_u32 v17, v3, v10, 1
	v_ashrrev_i32_e32 v13, 31, v12
	v_add_u32_e32 v3, 0x800, v2
	v_lshlrev_b64 v[54:55], 13, v[12:13]
	v_ashrrev_i32_e32 v12, 2, v3
	v_mul_lo_u32 v3, v12, 40
	v_add_lshl_u32 v18, v3, v10, 1
	v_ashrrev_i32_e32 v13, 31, v12
	v_add_u32_e32 v3, 0xa00, v2
	v_lshlrev_b64 v[56:57], 13, v[12:13]
	v_ashrrev_i32_e32 v12, 2, v3
	v_mul_lo_u32 v3, v12, 40
	v_add_lshl_u32 v19, v3, v10, 1
	v_ashrrev_i32_e32 v13, 31, v12
	v_add_u32_e32 v3, 0xc00, v2
	v_lshlrev_b64 v[58:59], 13, v[12:13]
	v_ashrrev_i32_e32 v12, 2, v3
	v_add_u32_e32 v2, 0xe00, v2
	v_mul_lo_u32 v3, v12, 40
	v_ashrrev_i32_e32 v2, 2, v2
	v_add_lshl_u32 v20, v3, v10, 1
	v_ashrrev_i32_e32 v13, 31, v12
	v_mul_lo_u32 v3, v2, 40
	v_mov_b32_e32 v9, v1
	v_lshlrev_b64 v[60:61], 13, v[12:13]
	v_add_lshl_u32 v12, v3, v10, 1
	v_ashrrev_i32_e32 v3, 31, v2
	v_lshlrev_b64 v[62:63], 13, v[2:3]
	v_lshl_add_u64 v[2:3], v[6:7], 0, v[8:9]
	s_mov_b64 s[8:9], 0xea40000
	v_lshl_add_u64 v[66:67], v[2:3], 0, s[8:9]
	s_lshl_b32 s8, s20, 1
	s_and_b32 s8, s8, -8
	s_add_i32 s8, s8, 0
	v_or_b32_e32 v14, 32, v4
	v_or_b32_e32 v16, 64, v4
	v_and_b32_e32 v230, 63, v153
	v_mul_u32_u24_e32 v230, 0x50, v230
	v_add_u32_e32 v143, s8, v230
	v_lshrrev_b32_e32 v230, 2, v153
	v_and_b32_e32 v231, 63, v230
	v_lshrrev_b32_e32 v230, 6, v230
	v_lshl_or_b32 v230, v231, 4, v230
	v_lshlrev_b32_e32 v48, 13, v230
	v_mov_b32_e32 v49, v1
	v_add_u32_e32 v50, 0x4000, v48
	v_mov_b32_e32 v51, v1
	v_add_u32_e32 v52, 0x8000, v48
	v_mov_b32_e32 v53, v1
	v_add_u32_e32 v54, 0xc000, v48
	v_mov_b32_e32 v55, v1
	v_add_u32_e32 v56, 0x10000, v48
	v_mov_b32_e32 v57, v1
	v_add_u32_e32 v58, 0x14000, v48
	v_mov_b32_e32 v59, v1
	v_add_u32_e32 v60, 0x18000, v48
	v_mov_b32_e32 v61, v1
	v_add_u32_e32 v62, 0x1c000, v48
	v_mov_b32_e32 v63, v1
	v_readlane_b32 s8, v254, 2
	v_or_b32_e32 v136, 4, v135
	v_or_b32_e32 v137, 8, v135
	v_or_b32_e32 v138, 12, v135
	v_or_b32_e32 v139, 16, v135
	v_or_b32_e32 v140, 20, v135
	v_or_b32_e32 v141, 24, v135
	v_or_b32_e32 v142, 28, v135
	v_lshl_add_u64 v[64:65], s[14:15], 0, v[8:9]
	s_add_i32 s18, s8, s21
	v_lshlrev_b32_e32 v0, 1, v4
	v_lshlrev_b32_e32 v68, 1, v14
	v_lshlrev_b32_e32 v70, 1, v16
	v_lshlrev_b32_e32 v72, 1, v8
	v_lshlrev_b32_e32 v74, 1, v10
	v_add_u32_e32 v144, 0, v15
	v_add_u32_e32 v145, 0, v5
	v_add_u32_e32 v146, 0, v11
	v_add_u32_e32 v147, 0, v17
	v_add_u32_e32 v148, 0, v18
	v_add_u32_e32 v149, 0, v19
	v_add_u32_e32 v150, 0, v20
	v_add_u32_e32 v151, 0, v12
	s_mov_b32 s19, s64
	s_branch .LBB0_785

; DI float bflo(unsigned w) { return __uint_as_float(w << 16); }
; DI float bfhi(unsigned w) { return __uint_as_float(w & 0xffff0000u); }
; DI void mla_finalize(PPtr p, int j, ldsp lds, int tid, int wave, int lane) {
;     ...
;             const float rq = rsqrtf(wave_sum(ssq) * (1.0f / QL) + EPS), rkv = rsqrtf(wave_sum(sskv) * (1.0f / KVL) + EPS);
;             float cs, sn;
;             { const int fi = lane & 15; const float inv = exp2f(-(float)fi * (13.287712379549449f / 16.0f));
;               const float ang = (float)p->pos[t] * inv; double rev = (double)ang * 0.15915494309189535; rev -= floor(rev); const float rv = (float)rev;
;               cs = __builtin_amdgcn_cosf(rv); sn = __builtin_amdgcn_sinf(rv); }
;             float cj[8], sj[8];
; #pragma unroll
;             for (int i = 0; i < 8; ++i) { cj[i] = __shfl(cs, 8 * (sub & 1) + i); sj[i] = __shfl(sn, 8 * (sub & 1) + i); }
; #pragma unroll
;             for (int which = 0; which < 2; ++which) {
;                 float v[24];
;                 if (which == 0) {
;                     const bf16_t* src = qraw + (size_t)t * 1536 + head * QKH;
; #pragma unroll
;                     for (int g = 0; g < 3; ++g) { const u32x4 w = *(const u32x4*)(src + 8 * (sub + 4 * g));
; #pragma unroll
;                         for (int i = 0; i < 4; ++i) { v[8 * g + 2 * i] = bflo(w[i]) * rq; v[8 * g + 2 * i + 1] = bfhi(w[i]) * rq; } }
.LBB0_785:
	s_mov_b32 s20, 0
	s_mov_b32 s14, s18
	global_load_dwordx4 v[230:233], v[46:47], off offset:16
	global_load_dwordx4 v[234:237], v[46:47], off
	global_load_dwordx4 v[238:241], v[46:47], off offset:144
	global_load_dwordx4 v[242:245], v[46:47], off offset:128
	global_load_dwordx4 v[246:249], v[46:47], off offset:272
	global_load_dwordx4 v[250:253], v[46:47], off offset:256
	s_branch .LBB0_787
.LBB0_786:
	s_or_b64 exec, exec, s[10:11]
	s_lshl_b64 s[10:11], s[14:15], 2
	s_add_u32 s10, s12, s10
	s_addc_u32 s11, s13, s11
	global_load_dword v6, v1, s[10:11]
	ds_bpermute_b32 v4, v39, v2
	ds_bpermute_b32 v5, v39, v3
	s_mov_b32 s10, 0x6dc9c883
	s_mov_b32 s11, 0x3fc45f30
	v_lshl_add_u64 v[106:107], v[64:65], 0, s[8:9]
	s_mov_b32 s8, 0x3b2aaaab
	s_waitcnt lgkmcnt(0)
	v_pk_add_f32 v[2:3], v[2:3], v[4:5]
	ds_bpermute_b32 v4, v77, v2
	ds_bpermute_b32 v5, v77, v3
	s_mov_b32 s9, 0x3b800000
	v_mov_b32_e32 v69, v1
	s_waitcnt lgkmcnt(0)
	v_pk_add_f32 v[2:3], v[2:3], v[4:5]
	ds_bpermute_b32 v4, v130, v2
	ds_bpermute_b32 v5, v130, v3
	s_waitcnt lgkmcnt(0)
	v_pk_add_f32 v[2:3], v[2:3], v[4:5]
	ds_bpermute_b32 v4, v131, v2
	ds_bpermute_b32 v5, v131, v3
	s_waitcnt lgkmcnt(0)
	v_pk_add_f32 v[2:3], v[2:3], v[4:5]
	ds_bpermute_b32 v4, v132, v2
	ds_bpermute_b32 v5, v132, v3
	s_waitcnt lgkmcnt(0)
	v_pk_add_f32 v[2:3], v[2:3], v[4:5]
	ds_bpermute_b32 v4, v133, v2
	ds_bpermute_b32 v5, v133, v3
	s_waitcnt lgkmcnt(0)
	v_pk_add_f32 v[2:3], v[2:3], v[4:5]
	s_nop 0
	v_pk_fma_f32 v[2:3], v[2:3], s[8:9], v[152:153] op_sel_hi:[1,1,0]
	s_waitcnt vmcnt(0)
	v_cvt_f32_i32_e32 v6, v6
	v_mul_f32_e32 v4, 0x4b800000, v3
	v_cmp_gt_f32_e64 s[8:9], s91, v2
	v_mul_f32_e32 v6, v134, v6
	v_cvt_f64_f32_e32 v[6:7], v6
	v_mul_f64 v[8:9], v[6:7], s[10:11]
	v_floor_f64_e32 v[8:9], v[8:9]
	v_fma_f64 v[6:7], v[6:7], s[10:11], -v[8:9]
	v_cvt_f32_f64_e32 v6, v[6:7]
	v_cos_f32_e32 v7, v6
	v_sin_f32_e32 v6, v6
	s_lshl_b64 s[10:11], s[14:15], 4
	v_or_b32_e32 v8, s10, v38
	ds_bpermute_b32 v100, v135, v7
	ds_bpermute_b32 v102, v135, v6
	ds_bpermute_b32 v101, v136, v7
	ds_bpermute_b32 v105, v136, v6
	ds_bpermute_b32 v94, v137, v7
	ds_bpermute_b32 v96, v137, v6
	ds_bpermute_b32 v95, v138, v7
	ds_bpermute_b32 v99, v138, v6
	ds_bpermute_b32 v88, v139, v7
	ds_bpermute_b32 v90, v139, v6
	ds_bpermute_b32 v89, v140, v7
	ds_bpermute_b32 v93, v140, v6
	ds_bpermute_b32 v80, v141, v7
	ds_bpermute_b32 v82, v141, v6
	ds_bpermute_b32 v81, v142, v7
	ds_bpermute_b32 v87, v142, v6
	v_mov_b64_e32 v[6:7], s[2:3]
	s_movk_i32 s10, 0xc0
	v_mad_u64_u32 v[84:85], s[22:23], v8, s10, v[6:7]
	v_mov_b32_e32 v6, 0xc0
	v_mad_i32_i24 v85, s11, v6, v85
	s_lshl_b64 s[10:11], s[14:15], 12
	v_lshl_add_u64 v[78:79], v[40:41], 0, s[10:11]
	v_cmp_gt_f32_e64 s[10:11], s91, v3
	s_nop 1
	v_cndmask_b32_e64 v3, v3, v4, s[10:11]
	v_rsq_f32_e32 v3, v3
	s_nop 0
	v_mul_f32_e32 v4, 0x45800000, v3
	v_cndmask_b32_e64 v76, v3, v4, s[10:11]
	v_mul_f32_e32 v3, 0x4b800000, v2
	v_cndmask_b32_e64 v2, v2, v3, s[8:9]
	v_rsq_f32_e32 v2, v2
	s_nop 0
	v_mul_f32_e32 v3, 0x45800000, v2
	v_cndmask_b32_e64 v86, v2, v3, s[8:9]
	v_mov_b32_e32 v2, 0xc00
	v_mad_i64_i32 v[2:3], s[8:9], s14, v2, v[66:67]
	s_mov_b64 s[8:9], 0x15a40000
	v_lshl_add_u64 v[110:111], v[84:85], 0, s[8:9]
	v_lshl_add_u64 v[168:169], v[110:111], 0, v[68:69]
	s_add_i32 s14, s14, 1
	v_mov_b32_e32 v34, v192
	v_mov_b32_e32 v35, v193
	v_mov_b32_e32 v36, v194
	v_mov_b32_e32 v37, v195
	v_lshlrev_b32_e32 v118, 16, v36
	v_and_b32_e32 v119, 0xffff0000, v36
	v_mov_b32_e32 v10, v196
	v_mov_b32_e32 v11, v197
	v_mov_b32_e32 v12, v198
	v_mov_b32_e32 v13, v199
	v_mov_b32_e32 v6, v206
	v_mov_b32_e32 v7, v207
	v_mov_b32_e32 v8, v208
	v_mov_b32_e32 v9, v209
	v_and_b32_e32 v2, 0xffff0000, v8
	v_lshlrev_b32_e32 v3, 16, v8
	s_waitcnt lgkmcnt(0)
	v_pk_mul_f32 v[108:109], v[86:87], v[2:3] op_sel_hi:[0,1]
	v_and_b32_e32 v2, 0xffff0000, v9
	v_lshlrev_b32_e32 v3, 16, v9
	v_pk_mul_f32 v[8:9], v[86:87], v[2:3] op_sel_hi:[0,1]
	global_load_dwordx4 v[22:25], v[44:45], off
	global_load_dwordx4 v[26:29], v[44:45], off offset:16
	global_load_dwordx4 v[18:21], v[44:45], off offset:128
	global_load_dwordx4 v[14:17], v[44:45], off offset:144
	global_load_dwordx4 v[2:5], v[44:45], off offset:272
	global_load_dwordx4 v[30:33], v[44:45], off offset:256
	v_lshlrev_b32_e32 v120, 16, v34
	v_and_b32_e32 v121, 0xffff0000, v34
	v_lshlrev_b32_e32 v116, 16, v37
	v_and_b32_e32 v117, 0xffff0000, v37
	v_pk_mul_f32 v[36:37], v[86:87], v[118:119] op_sel_hi:[0,1]
	v_lshlrev_b32_e32 v118, 16, v35
	v_and_b32_e32 v119, 0xffff0000, v35
	v_pk_mul_f32 v[120:121], v[86:87], v[120:121] op_sel_hi:[0,1]
	v_pk_mul_f32 v[118:119], v[86:87], v[118:119] op_sel_hi:[0,1]
	v_pk_mul_f32 v[156:157], v[120:121], v[120:121]
	v_pk_mul_f32 v[128:129], v[118:119], v[118:119]
	v_add_f32_e32 v71, v156, v157
	v_add_f32_e32 v71, v128, v71
	v_pk_mul_f32 v[126:127], v[36:37], v[36:37]
	v_add_f32_e32 v71, v129, v71
	v_pk_mul_f32 v[116:117], v[86:87], v[116:117] op_sel_hi:[0,1]
	v_add_f32_e32 v71, v126, v71
	v_pk_mul_f32 v[124:125], v[116:117], v[116:117]
	v_lshlrev_b32_e32 v166, 16, v10
	v_and_b32_e32 v167, 0xffff0000, v10
	v_add_f32_e32 v71, v127, v71
	v_lshlrev_b32_e32 v162, 16, v11
	v_and_b32_e32 v163, 0xffff0000, v11
	v_pk_mul_f32 v[10:11], v[86:87], v[166:167] op_sel_hi:[0,1]
	v_add_f32_e32 v71, v124, v71
	v_pk_mul_f32 v[166:167], v[10:11], v[10:11]
	v_add_f32_e32 v71, v125, v71
	v_pk_mul_f32 v[162:163], v[86:87], v[162:163] op_sel_hi:[0,1]
	v_add_f32_e32 v71, v166, v71
	v_lshlrev_b32_e32 v160, 16, v12
	v_and_b32_e32 v161, 0xffff0000, v12
	v_pk_mul_f32 v[164:165], v[162:163], v[162:163]
	v_add_f32_e32 v71, v167, v71
	v_lshlrev_b32_e32 v122, 16, v13
	v_and_b32_e32 v123, 0xffff0000, v13
	v_pk_mul_f32 v[12:13], v[86:87], v[160:161] op_sel_hi:[0,1]
	v_add_f32_e32 v71, v164, v71
	v_pk_mul_f32 v[160:161], v[12:13], v[12:13]
	v_add_f32_e32 v71, v165, v71
	v_pk_mul_f32 v[122:123], v[86:87], v[122:123] op_sel_hi:[0,1]
	v_add_f32_e32 v71, v160, v71
	v_pk_mul_f32 v[158:159], v[122:123], v[122:123]
	v_lshlrev_b32_e32 v174, 16, v6
	v_and_b32_e32 v175, 0xffff0000, v6
	v_add_f32_e32 v71, v161, v71
	v_lshlrev_b32_e32 v170, 16, v7
	v_and_b32_e32 v171, 0xffff0000, v7
	v_pk_mul_f32 v[6:7], v[86:87], v[174:175] op_sel_hi:[0,1]
	v_add_f32_e32 v71, v158, v71
	v_pk_mul_f32 v[174:175], v[6:7], v[6:7]
	v_add_f32_e32 v71, v159, v71
	v_pk_mul_f32 v[170:171], v[86:87], v[170:171] op_sel_hi:[0,1]
	v_add_f32_e32 v71, v174, v71
	v_pk_mul_f32 v[172:173], v[170:171], v[170:171]
	v_add_f32_e32 v71, v175, v71
	v_add_f32_e32 v71, v172, v71
	v_pk_mul_f32 v[112:113], v[108:109], v[108:109]
	v_add_f32_e32 v71, v173, v71
	v_add_f32_e32 v71, v113, v71
	v_pk_mul_f32 v[114:115], v[8:9], v[8:9]
	v_add_f32_e32 v71, v112, v71
	v_add_f32_e32 v71, v115, v71
	v_add_f32_e32 v71, v114, v71
	ds_bpermute_b32 v73, v39, v71
	v_lshl_add_u64 v[34:35], v[110:111], 0, v[0:1]
	s_waitcnt lgkmcnt(0)
; DI unsigned pk2(float lo, float hi) { f32x2 v = {lo, hi}; bf16x2_t b = __builtin_convertvector(v, bf16x2_t); return __builtin_bit_cast(unsigned, b); }
; DI float bflo(unsigned w) { return __uint_as_float(w << 16); }
; DI float bfhi(unsigned w) { return __uint_as_float(w & 0xffff0000u); }
; DI void mla_finalize(PPtr p, int j, ldsp lds, int tid, int wave, int lane) {
;     ...
;                     const bf16_t* src = kvraw + (size_t)t * 2048 + head * 128;
; #pragma unroll
;                     for (int g = 0; g < 2; ++g) { const u32x4 w = *(const u32x4*)(src + 8 * (sub + 4 * g));
; #pragma unroll
;                         for (int i = 0; i < 4; ++i) { v[8 * g + 2 * i] = bflo(w[i]) * rkv; v[8 * g + 2 * i + 1] = bfhi(w[i]) * rkv; } }
;                     const u32x4 w = *(const u32x4*)(aout + (size_t)t * ADIMP + QL + KVL + 8 * sub);
; #pragma unroll
;                     for (int i = 0; i < 4; ++i) { v[16 + 2 * i] = bflo(w[i]); v[16 + 2 * i + 1] = bfhi(w[i]); }
;     ...
;                 float ss = 0.f;
; #pragma unroll
;                 for (int i = 0; i < 24; ++i) ss += v[i] * v[i];
;                 ss += __shfl_xor(ss, 1); ss += __shfl_xor(ss, 2);
;                 const float rs = rsqrtf(ss * (1.0f / QKH) + EPS);
;                 const float* gn = which == 0 ? qg : kg;
; #pragma unroll
;                 for (int g = 0; g < 3; ++g) { const f32x4 g0 = *(const f32x4*)(gn + 8 * (sub + 4 * g)), g1 = *(const f32x4*)(gn + 8 * (sub + 4 * g) + 4);
; #pragma unroll
;                     for (int i = 0; i < 4; ++i) { v[8 * g + i] *= rs * g0[i]; v[8 * g + 4 + i] *= rs * g1[i]; } }
; #pragma unroll
;                 for (int i = 0; i < 8; ++i) { const float mine = v[16 + i], other = __shfl_xor(mine, 2);
;                     v[16 + i] = (sub < 2) ? (mine * cj[i] - other * sj[i]) : (other * sj[i] + mine * cj[i]); }
;                 const float osc = which == 0 ? QSCALE : 1.0f;
;                 bf16_t* dst = (which == 0 ? Qb : Kb) + ((size_t)t * HEADS + head) * QKH;
; #pragma unroll
;                 for (int g = 0; g < 3; ++g) { u32x4 w;
; #pragma unroll
;                     for (int i = 0; i < 4; ++i) w[i] = pk2(v[8 * g + 2 * i] * osc, v[8 * g + 2 * i + 1] * osc);
;                     *(u32x4*)(dst + 8 * (sub + 4 * g)) = w; }
	v_add_f32_e32 v71, v71, v73
	ds_bpermute_b32 v73, v77, v71
	s_waitcnt lgkmcnt(0)
	v_add_f32_e32 v71, v71, v73
	v_fmamk_f32 v71, v71, 0x3c2aaaab, v152
	v_cmp_gt_f32_e64 s[8:9], s91, v71
	v_mul_f32_e32 v73, 0x4b800000, v71
	s_nop 0
	v_cndmask_b32_e64 v71, v71, v73, s[8:9]
	v_rsq_f32_e32 v71, v71
	s_nop 0
	v_mul_f32_e32 v73, 0x45800000, v71
	v_cndmask_b32_e64 v86, v71, v73, s[8:9]
	s_waitcnt vmcnt(3)
	v_pk_mul_f32 v[18:19], v[18:19], v[86:87] op_sel_hi:[1,0]
	v_pk_mul_f32 v[22:23], v[22:23], v[86:87] op_sel_hi:[1,0]
	v_pk_mul_f32 v[18:19], v[10:11], v[18:19]
	s_waitcnt vmcnt(2)
	v_pk_mul_f32 v[10:11], v[14:15], v[86:87] op_sel_hi:[1,0]
	v_pk_mul_f32 v[24:25], v[24:25], v[86:87] op_sel_hi:[1,0]
	v_pk_mul_f32 v[14:15], v[12:13], v[10:11]
	v_pk_mul_f32 v[10:11], v[20:21], v[86:87] op_sel_hi:[1,0]
	v_pk_mul_f32 v[22:23], v[120:121], v[22:23]
	v_pk_mul_f32 v[20:21], v[162:163], v[10:11]
	v_pk_mul_f32 v[10:11], v[16:17], v[86:87] op_sel_hi:[1,0]
	v_pk_mul_f32 v[26:27], v[26:27], v[86:87] op_sel_hi:[1,0]
	v_pk_mul_f32 v[16:17], v[122:123], v[10:11]
	s_waitcnt vmcnt(0)
	v_pk_mul_f32 v[10:11], v[30:31], v[86:87] op_sel_hi:[1,0]
	v_pk_mul_f32 v[24:25], v[118:119], v[24:25]
	v_pk_mul_f32 v[6:7], v[6:7], v[10:11]
	v_pk_mul_f32 v[10:11], v[32:33], v[86:87] op_sel_hi:[1,0]
	ds_bpermute_b32 v104, v77, v6
	ds_bpermute_b32 v103, v77, v7
	v_pk_mul_f32 v[10:11], v[170:171], v[10:11]
	ds_bpermute_b32 v98, v77, v10
	ds_bpermute_b32 v97, v77, v11
	v_pk_mul_f32 v[28:29], v[28:29], v[86:87] op_sel_hi:[1,0]
	s_waitcnt lgkmcnt(2)
	v_pk_mul_f32 v[12:13], v[104:105], v[102:103]
	v_pk_mul_f32 v[26:27], v[36:37], v[26:27]
	v_cndmask_b32_e64 v13, v13, -v13, s[6:7]
	v_cndmask_b32_e64 v12, v12, -v12, s[6:7]
	v_pk_fma_f32 v[6:7], v[6:7], v[100:101], v[12:13]
	s_waitcnt lgkmcnt(0)
	v_pk_mul_f32 v[12:13], v[98:99], v[96:97]
	v_pk_mul_f32 v[28:29], v[116:117], v[28:29]
	v_cndmask_b32_e64 v13, v13, -v13, s[6:7]
	v_cndmask_b32_e64 v12, v12, -v12, s[6:7]
	v_pk_fma_f32 v[30:31], v[10:11], v[94:95], v[12:13]
	v_pk_mul_f32 v[10:11], v[22:23], s[86:87] op_sel_hi:[1,0]
	v_pk_mul_f32 v[12:13], v[24:25], s[86:87] op_sel_hi:[1,0]
	v_pk_mul_f32 v[2:3], v[2:3], v[86:87] op_sel_hi:[1,0]
	v_cvt_pk_bf16_f32 v10, v10, v11
	v_cvt_pk_bf16_f32 v11, v12, v13
	v_pk_mul_f32 v[12:13], v[26:27], s[86:87] op_sel_hi:[1,0]
	v_pk_mul_f32 v[22:23], v[28:29], s[86:87] op_sel_hi:[1,0]
	v_pk_mul_f32 v[2:3], v[108:109], v[2:3] op_sel:[1,0] op_sel_hi:[0,1]
	v_cvt_pk_bf16_f32 v12, v12, v13
	v_cvt_pk_bf16_f32 v13, v22, v23
	ds_bpermute_b32 v92, v77, v2
	ds_bpermute_b32 v91, v77, v3
	global_store_dwordx4 v[34:35], v[10:13], off
	v_pk_mul_f32 v[6:7], v[6:7], s[86:87] op_sel_hi:[1,0]
	v_mov_b32_e32 v71, v1
	v_pk_mul_f32 v[10:11], v[18:19], s[86:87] op_sel_hi:[1,0]
	v_pk_mul_f32 v[12:13], v[20:21], s[86:87] op_sel_hi:[1,0]
	v_cvt_pk_bf16_f32 v10, v10, v11
	v_cvt_pk_bf16_f32 v11, v12, v13
	v_pk_mul_f32 v[12:13], v[14:15], s[86:87] op_sel_hi:[1,0]
	v_pk_mul_f32 v[14:15], v[16:17], s[86:87] op_sel_hi:[1,0]
	v_cvt_pk_bf16_f32 v12, v12, v13
	v_cvt_pk_bf16_f32 v13, v14, v15
	global_store_dwordx4 v[168:169], v[10:13], off
	v_mov_b32_e32 v103, v105
	v_mov_b32_e32 v97, v99
	v_cvt_pk_bf16_f32 v10, v6, v7
	v_pk_mul_f32 v[6:7], v[30:31], s[86:87] op_sel_hi:[1,0]
	s_nop 0
	v_cvt_pk_bf16_f32 v11, v6, v7
	s_waitcnt lgkmcnt(0)
	v_pk_mul_f32 v[6:7], v[92:93], v[90:91]
	v_mov_b32_e32 v91, v93
	v_cndmask_b32_e64 v7, v7, -v7, s[6:7]
	v_cndmask_b32_e64 v6, v6, -v6, s[6:7]
	v_pk_fma_f32 v[2:3], v[2:3], v[88:89], v[6:7]
	s_nop 0
	v_pk_mul_f32 v[2:3], v[2:3], s[86:87] op_sel_hi:[1,0]
	s_nop 0
	v_cvt_pk_bf16_f32 v12, v2, v3
	v_pk_mul_f32 v[2:3], v[4:5], v[86:87] op_sel_hi:[1,0]
	s_nop 0
	v_pk_mul_f32 v[2:3], v[8:9], v[2:3] op_sel:[1,0] op_sel_hi:[0,1]
	ds_bpermute_b32 v86, v77, v2
	ds_bpermute_b32 v83, v77, v3
	s_waitcnt lgkmcnt(0)
	v_pk_mul_f32 v[4:5], v[86:87], v[82:83]
	s_nop 0
	v_cndmask_b32_e64 v5, v5, -v5, s[6:7]
	v_cndmask_b32_e64 v4, v4, -v4, s[6:7]
	v_pk_fma_f32 v[2:3], v[2:3], v[80:81], v[4:5]
	v_mov_b32_e32 v83, v87
	v_pk_mul_f32 v[2:3], v[2:3], s[86:87] op_sel_hi:[1,0]
	v_mov_b32_e32 v6, v188
	v_mov_b32_e32 v7, v189
	v_mov_b32_e32 v8, v190
	v_mov_b32_e32 v9, v191
	v_lshlrev_b32_e32 v166, 16, v6
	v_cvt_pk_bf16_f32 v13, v2, v3
	v_lshl_add_u64 v[2:3], v[110:111], 0, v[70:71]
	global_store_dwordx4 v[2:3], v[10:13], off
	v_and_b32_e32 v167, 0xffff0000, v6
	v_lshlrev_b32_e32 v162, 16, v7
	v_lshl_add_u64 v[10:11], v[78:79], 0, v[0:1]
	v_and_b32_e32 v163, 0xffff0000, v7
	v_pk_mul_f32 v[6:7], v[166:167], v[166:167]
	v_pk_mul_f32 v[164:165], v[162:163], v[162:163]
	v_and_b32_e32 v10, 0xffff0000, v8
	v_lshlrev_b32_e32 v11, 16, v8
	v_pk_mul_f32 v[32:33], v[10:11], v[10:11]
	v_and_b32_e32 v8, 0xffff0000, v9
	v_lshlrev_b32_e32 v9, 16, v9
	v_pk_mul_f32 v[34:35], v[8:9], v[8:9]
	v_mov_b32_e32 v2, v210
	v_mov_b32_e32 v3, v211
	v_mov_b32_e32 v4, v212
	v_mov_b32_e32 v5, v213
	v_lshlrev_b32_e32 v24, 16, v5
	v_and_b32_e32 v25, 0xffff0000, v5
	v_pk_mul_f32 v[36:37], v[76:77], v[24:25] op_sel_hi:[0,1]
	v_lshlrev_b32_e32 v24, 16, v4
	v_and_b32_e32 v25, 0xffff0000, v4
	v_lshlrev_b32_e32 v4, 16, v3
	v_and_b32_e32 v5, 0xffff0000, v3
	v_pk_mul_f32 v[112:113], v[76:77], v[4:5] op_sel_hi:[0,1]
	v_lshlrev_b32_e32 v4, 16, v2
	v_and_b32_e32 v5, 0xffff0000, v2
	v_mov_b32_e32 v12, v218
	v_mov_b32_e32 v13, v219
	v_mov_b32_e32 v14, v220
	v_mov_b32_e32 v15, v221
	v_lshlrev_b32_e32 v2, 16, v15
	v_and_b32_e32 v3, 0xffff0000, v15
	v_pk_mul_f32 v[120:121], v[76:77], v[2:3] op_sel_hi:[0,1]
	v_lshlrev_b32_e32 v2, 16, v14
	v_and_b32_e32 v3, 0xffff0000, v14
	v_pk_mul_f32 v[124:125], v[76:77], v[2:3] op_sel_hi:[0,1]
	v_lshlrev_b32_e32 v2, 16, v13
	v_and_b32_e32 v3, 0xffff0000, v13
; DI void mla_finalize(PPtr p, int j, ldsp lds, int tid, int wave, int lane) {
;     ...
;                 float ss = 0.f;
; #pragma unroll
;                 for (int i = 0; i < 24; ++i) ss += v[i] * v[i];
;                 ss += __shfl_xor(ss, 1); ss += __shfl_xor(ss, 2);
;                 const float rs = rsqrtf(ss * (1.0f / QKH) + EPS);
;                 const float* gn = which == 0 ? qg : kg;
; #pragma unroll
;                 for (int g = 0; g < 3; ++g) { const f32x4 g0 = *(const f32x4*)(gn + 8 * (sub + 4 * g)), g1 = *(const f32x4*)(gn + 8 * (sub + 4 * g) + 4);
; #pragma unroll
;                     for (int i = 0; i < 4; ++i) { v[8 * g + i] *= rs * g0[i]; v[8 * g + 4 + i] *= rs * g1[i]; } }
; #pragma unroll
;                 for (int i = 0; i < 8; ++i) { const float mine = v[16 + i], other = __shfl_xor(mine, 2);
;                     v[16 + i] = (sub < 2) ? (mine * cj[i] - other * sj[i]) : (other * sj[i] + mine * cj[i]); }
	v_pk_mul_f32 v[128:129], v[76:77], v[2:3] op_sel_hi:[0,1]
	v_lshlrev_b32_e32 v2, 16, v12
	v_and_b32_e32 v3, 0xffff0000, v12
	v_pk_mul_f32 v[108:109], v[76:77], v[24:25] op_sel_hi:[0,1]
	v_pk_mul_f32 v[116:117], v[76:77], v[4:5] op_sel_hi:[0,1]
	v_pk_mul_f32 v[158:159], v[76:77], v[2:3] op_sel_hi:[0,1]
	v_pk_mul_f32 v[118:119], v[116:117], v[116:117]
	v_pk_mul_f32 v[114:115], v[112:113], v[112:113]
	v_add_f32_e32 v73, v118, v119
	v_add_f32_e32 v73, v114, v73
	v_pk_mul_f32 v[110:111], v[108:109], v[108:109]
	v_add_f32_e32 v73, v115, v73
	v_add_f32_e32 v73, v110, v73
	v_pk_mul_f32 v[106:107], v[36:37], v[36:37]
	v_add_f32_e32 v73, v111, v73
	v_add_f32_e32 v73, v106, v73
	v_pk_mul_f32 v[160:161], v[158:159], v[158:159]
	v_add_f32_e32 v73, v107, v73
	v_add_f32_e32 v73, v160, v73
	v_pk_mul_f32 v[156:157], v[128:129], v[128:129]
	v_add_f32_e32 v73, v161, v73
	v_add_f32_e32 v73, v156, v73
	v_pk_mul_f32 v[126:127], v[124:125], v[124:125]
	v_add_f32_e32 v73, v157, v73
	v_add_f32_e32 v73, v126, v73
	v_pk_mul_f32 v[122:123], v[120:121], v[120:121]
	v_add_f32_e32 v73, v127, v73
	v_add_f32_e32 v73, v122, v73
	v_add_f32_e32 v73, v123, v73
	v_add_f32_e32 v6, v6, v73
	v_add_f32_e32 v6, v7, v6
	v_add_f32_e32 v6, v164, v6
	v_add_f32_e32 v6, v165, v6
	v_add_f32_e32 v6, v33, v6
	v_add_f32_e32 v6, v32, v6
	v_add_f32_e32 v6, v35, v6
	v_add_f32_e32 v6, v34, v6
	ds_bpermute_b32 v7, v39, v6
	v_mov_b32_e32 v73, v1
	s_waitcnt lgkmcnt(0)
	v_add_f32_e32 v6, v6, v7
	ds_bpermute_b32 v7, v77, v6
	s_waitcnt lgkmcnt(0)
	v_add_f32_e32 v6, v6, v7
	v_fmamk_f32 v6, v6, 0x3c2aaaab, v152
	v_cmp_gt_f32_e64 s[8:9], s91, v6
	v_mul_f32_e32 v7, 0x4b800000, v6
	s_nop 0
	v_cndmask_b32_e64 v6, v6, v7, s[8:9]
	v_rsq_f32_e32 v6, v6
	s_nop 0
	v_mul_f32_e32 v7, 0x45800000, v6
	v_cndmask_b32_e64 v6, v6, v7, s[8:9]
	v_mov_b32_e32 v16, v230
	v_mov_b32_e32 v17, v231
	v_mov_b32_e32 v18, v232
	v_mov_b32_e32 v19, v233
	v_mov_b32_e32 v20, v234
	v_mov_b32_e32 v21, v235
	v_mov_b32_e32 v22, v236
	v_mov_b32_e32 v23, v237
	v_pk_mul_f32 v[20:21], v[20:21], v[6:7] op_sel_hi:[1,0]
	v_pk_mul_f32 v[16:17], v[16:17], v[6:7] op_sel_hi:[1,0]
	v_pk_mul_f32 v[22:23], v[22:23], v[6:7] op_sel_hi:[1,0]
	v_pk_mul_f32 v[18:19], v[18:19], v[6:7] op_sel_hi:[1,0]
	s_mov_b64 s[8:9], 0x18a40000
	v_pk_mul_f32 v[20:21], v[116:117], v[20:21]
	v_pk_mul_f32 v[16:17], v[108:109], v[16:17]
	v_pk_mul_f32 v[22:23], v[112:113], v[22:23]
	v_pk_mul_f32 v[18:19], v[36:37], v[18:19]
	v_mov_b32_e32 v24, v238
	v_mov_b32_e32 v25, v239
	v_mov_b32_e32 v26, v240
	v_mov_b32_e32 v27, v241
	v_pk_mul_f32 v[24:25], v[24:25], v[6:7] op_sel_hi:[1,0]
	v_mov_b32_e32 v28, v242
	v_mov_b32_e32 v29, v243
	v_mov_b32_e32 v30, v244
	v_mov_b32_e32 v31, v245
	v_pk_mul_f32 v[28:29], v[28:29], v[6:7] op_sel_hi:[1,0]
	v_mov_b32_e32 v2, v246
	v_mov_b32_e32 v3, v247
	v_mov_b32_e32 v4, v248
	v_mov_b32_e32 v5, v249
	v_pk_mul_f32 v[2:3], v[2:3], v[6:7] op_sel_hi:[1,0]
	v_mov_b32_e32 v12, v250
	v_mov_b32_e32 v13, v251
	v_mov_b32_e32 v14, v252
	v_mov_b32_e32 v15, v253
	v_pk_mul_f32 v[12:13], v[12:13], v[6:7] op_sel_hi:[1,0]
	v_pk_mul_f32 v[2:3], v[2:3], v[10:11] op_sel:[0,1] op_sel_hi:[1,0]
	ds_bpermute_b32 v10, v77, v2
	ds_bpermute_b32 v11, v77, v3
	v_pk_mul_f32 v[12:13], v[12:13], v[166:167]
	ds_bpermute_b32 v32, v77, v12
	ds_bpermute_b32 v33, v77, v13
	v_pk_mul_f32 v[14:15], v[14:15], v[6:7] op_sel_hi:[1,0]
	s_waitcnt lgkmcnt(2)
	v_pk_mul_f32 v[10:11], v[90:91], v[10:11]
	v_pk_mul_f32 v[14:15], v[14:15], v[162:163]
	v_cndmask_b32_e64 v11, v11, -v11, s[6:7]
	v_cndmask_b32_e64 v10, v10, -v10, s[6:7]
	v_pk_fma_f32 v[10:11], v[2:3], v[88:89], v[10:11]
	v_pk_mul_f32 v[2:3], v[4:5], v[6:7] op_sel_hi:[1,0]
	s_waitcnt lgkmcnt(0)
	v_pk_mul_f32 v[32:33], v[102:103], v[32:33]
	v_pk_mul_f32 v[2:3], v[2:3], v[8:9] op_sel:[0,1] op_sel_hi:[1,0]
	v_cndmask_b32_e64 v33, v33, -v33, s[6:7]
	v_cndmask_b32_e64 v32, v32, -v32, s[6:7]
	ds_bpermute_b32 v4, v77, v2
	ds_bpermute_b32 v5, v77, v3
	v_pk_fma_f32 v[12:13], v[12:13], v[100:101], v[32:33]
	ds_bpermute_b32 v32, v77, v14
	ds_bpermute_b32 v33, v77, v15
	v_pk_mul_f32 v[30:31], v[30:31], v[6:7] op_sel_hi:[1,0]
	s_waitcnt lgkmcnt(2)
	v_pk_mul_f32 v[4:5], v[82:83], v[4:5]
	v_pk_mul_f32 v[26:27], v[26:27], v[6:7] op_sel_hi:[1,0]
	v_cndmask_b32_e64 v5, v5, -v5, s[6:7]
	s_waitcnt lgkmcnt(0)
; #define LAS __attribute__((address_space(3)))
; DI unsigned pk2(float lo, float hi) { f32x2 v = {lo, hi}; bf16x2_t b = __builtin_convertvector(v, bf16x2_t); return __builtin_bit_cast(unsigned, b); }
; DI bf16_t f2bf(float v) { return (bf16_t)(pk2(v, 0.f) & 0xffffu); }
; DI float bflo(unsigned w) { return __uint_as_float(w << 16); }
; DI float bfhi(unsigned w) { return __uint_as_float(w & 0xffff0000u); }
; DI void mla_finalize(PPtr p, int j, ldsp lds, int tid, int wave, int lane) {
;     ...
;         for (int rr = 0; rr < 4; ++rr) {
;             const int tok = wave * 4 + rr, t = t0 + tok;
;             float ssq = 0.f, sskv = 0.f;
;             if (lane < 48) { const u32x4 w = *(const u32x4*)(aout + (size_t)t * ADIMP + 8 * lane);
; #pragma unroll
;                 for (int i = 0; i < 4; ++i) { const float a = bflo(w[i]), c = bfhi(w[i]); ssq += a * a + c * c; } }
;             if (lane < 32) { const u32x4 w = *(const u32x4*)(aout + (size_t)t * ADIMP + QL + 8 * lane);
; #pragma unroll
;                 for (int i = 0; i < 4; ++i) { const float a = bflo(w[i]), c = bfhi(w[i]); sskv += a * a + c * c; } }
;     ...
;                 bf16_t* dst = (which == 0 ? Qb : Kb) + ((size_t)t * HEADS + head) * QKH;
; #pragma unroll
;                 for (int g = 0; g < 3; ++g) { u32x4 w;
; #pragma unroll
;                     for (int i = 0; i < 4; ++i) w[i] = pk2(v[8 * g + 2 * i] * osc, v[8 * g + 2 * i + 1] * osc);
;                     *(u32x4*)(dst + 8 * (sub + 4 * g)) = w; }
;             }
;             { const bf16_t* src = kvraw + (size_t)t * 2048 + head * 128 + 64 + 16 * sub;
; #pragma unroll
;               for (int g = 0; g < 2; ++g) { const u32x4 w = *(const u32x4*)(src + 8 * g);
; #pragma unroll
;                   for (int i = 0; i < 4; ++i) { const int d = head * 64 + 16 * sub + 8 * g + 2 * i;
;                       *(LAS bf16_t*)(lds + ((d) * VTP + tok) * 2) = f2bf(bflo(w[i]) * rkv);
;                       *(LAS bf16_t*)(lds + ((d + 1) * VTP + tok) * 2) = f2bf(bfhi(w[i]) * rkv); } } }
	v_pk_mul_f32 v[32:33], v[96:97], v[32:33]
	v_cndmask_b32_e64 v4, v4, -v4, s[6:7]
	v_lshl_add_u64 v[8:9], v[84:85], 0, s[8:9]
	v_pk_mul_f32 v[28:29], v[158:159], v[28:29]
	v_pk_mul_f32 v[24:25], v[124:125], v[24:25]
	v_pk_mul_f32 v[30:31], v[128:129], v[30:31]
	v_pk_mul_f32 v[26:27], v[120:121], v[26:27]
	v_cndmask_b32_e64 v33, v33, -v33, s[6:7]
	v_cndmask_b32_e64 v32, v32, -v32, s[6:7]
	v_pk_fma_f32 v[6:7], v[2:3], v[80:81], v[4:5]
	v_cvt_pk_bf16_f32 v2, v20, v21
	v_cvt_pk_bf16_f32 v3, v22, v23
	v_cvt_pk_bf16_f32 v4, v16, v17
	v_cvt_pk_bf16_f32 v5, v18, v19
	v_lshl_add_u64 v[16:17], v[8:9], 0, v[0:1]
	v_pk_fma_f32 v[14:15], v[14:15], v[94:95], v[32:33]
	global_store_dwordx4 v[16:17], v[2:5], off
	v_lshl_add_u64 v[16:17], v[8:9], 0, v[68:69]
	s_nop 0
	v_cvt_pk_bf16_f32 v2, v28, v29
	v_cvt_pk_bf16_f32 v3, v30, v31
	v_cvt_pk_bf16_f32 v4, v24, v25
	v_cvt_pk_bf16_f32 v5, v26, v27
	global_store_dwordx4 v[16:17], v[2:5], off
	s_nop 1
	v_cvt_pk_bf16_f32 v2, v12, v13
	v_cvt_pk_bf16_f32 v3, v14, v15
	v_cvt_pk_bf16_f32 v4, v10, v11
	v_cvt_pk_bf16_f32 v5, v6, v7
	v_lshl_add_u64 v[6:7], v[8:9], 0, v[70:71]
	global_store_dwordx4 v[6:7], v[2:5], off
	v_lshl_add_u64 v[6:7], v[78:79], 0, v[72:73]
	s_nop 0
	v_add_u32_e32 v11, s20, v143
	v_add_u32_e32 v176, 0xa000, v11
	s_add_i32 s20, s20, 2
	s_cmp_eq_u32 s20, 8
	v_mov_b32_e32 v2, v222
	v_mov_b32_e32 v3, v223
	v_mov_b32_e32 v4, v224
	v_mov_b32_e32 v5, v225
	v_mov_b32_e32 v6, v226
	v_mov_b32_e32 v7, v227
	v_mov_b32_e32 v8, v228
	v_mov_b32_e32 v9, v229
	v_lshlrev_b32_e32 v10, 16, v6
	v_and_b32_e32 v6, 0xffff0000, v6
	v_mul_f32_e32 v6, v76, v6
	v_cvt_pk_bf16_f32 v6, v6, s0
	ds_write_b16 v11, v6 offset:5120
	v_lshlrev_b32_e32 v6, 16, v7
	v_mul_f32_e32 v6, v76, v6
	v_cvt_pk_bf16_f32 v6, v6, s0
	ds_write_b16 v11, v6 offset:10240
	v_and_b32_e32 v6, 0xffff0000, v7
	v_mul_f32_e32 v6, v76, v6
	v_cvt_pk_bf16_f32 v6, v6, s0
	ds_write_b16 v11, v6 offset:15360
	v_lshlrev_b32_e32 v6, 16, v8
	v_mul_f32_e32 v6, v76, v6
	v_cvt_pk_bf16_f32 v6, v6, s0
	ds_write_b16 v11, v6 offset:20480
	v_and_b32_e32 v6, 0xffff0000, v8
	v_mul_f32_e32 v6, v76, v6
	v_cvt_pk_bf16_f32 v6, v6, s0
	ds_write_b16 v11, v6 offset:25600
	v_lshlrev_b32_e32 v6, 16, v9
	v_mul_f32_e32 v6, v76, v6
	v_cvt_pk_bf16_f32 v6, v6, s0
	ds_write_b16 v11, v6 offset:30720
	v_and_b32_e32 v6, 0xffff0000, v9
	v_mul_f32_e32 v6, v76, v6
	v_cvt_pk_bf16_f32 v6, v6, s0
	ds_write_b16 v11, v6 offset:35840
	v_lshlrev_b32_e32 v6, 16, v2
	v_and_b32_e32 v2, 0xffff0000, v2
	v_mul_f32_e32 v2, v76, v2
	v_cvt_pk_bf16_f32 v2, v2, s0
	ds_write_b16 v176, v2 offset:5120
	v_lshlrev_b32_e32 v2, 16, v3
	v_mul_f32_e32 v2, v76, v2
	v_cvt_pk_bf16_f32 v2, v2, s0
	ds_write_b16 v176, v2 offset:10240
	v_and_b32_e32 v2, 0xffff0000, v3
	v_mul_f32_e32 v2, v76, v2
	v_cvt_pk_bf16_f32 v2, v2, s0
	ds_write_b16 v176, v2 offset:15360
	v_lshlrev_b32_e32 v2, 16, v4
	v_mul_f32_e32 v2, v76, v2
	v_cvt_pk_bf16_f32 v2, v2, s0
	ds_write_b16 v176, v2 offset:20480
	v_and_b32_e32 v2, 0xffff0000, v4
	v_mul_f32_e32 v2, v76, v2
	v_cvt_pk_bf16_f32 v2, v2, s0
	ds_write_b16 v176, v2 offset:25600
	v_lshlrev_b32_e32 v2, 16, v5
	v_mul_f32_e32 v2, v76, v2
	v_cvt_pk_bf16_f32 v2, v2, s0
	ds_write_b16 v176, v2 offset:30720
	v_and_b32_e32 v2, 0xffff0000, v5
	v_mul_f32_e32 v10, v76, v10
	v_mul_f32_e32 v6, v76, v6
	v_mul_f32_e32 v2, v76, v2
	v_cvt_pk_bf16_f32 v10, v10, s0
	v_cvt_pk_bf16_f32 v6, v6, s0
	v_cvt_pk_bf16_f32 v2, v2, s0
	ds_write_b16 v11, v10
	ds_write_b16 v176, v6
	ds_write_b16 v176, v2 offset:35840
	s_cbranch_scc1 .LBB0_784
.LBB0_787:
	s_mul_hi_i32 s9, s14, 0x600
	s_mul_i32 s8, s14, 0x600
	v_mov_b32_e32 v3, 0
	v_lshl_add_u64 v[4:5], v[42:43], 0, s[8:9]
	v_mov_b32_e32 v2, 0
	global_load_dwordx4 v[180:183], v[4:5], off
	global_load_dwordx4 v[184:187], v[4:5], off offset:768
	v_lshl_add_u64 v[176:177], v[64:65], 0, s[8:9]
	s_mul_i32 s28, s14, 0xc00
	s_mov_b32 s29, 0
	global_load_dwordx4 v[188:191], v[176:177], off offset:1280
	v_lshl_add_u64 v[176:177], v[66:67], 0, s[28:29]
	s_lshl_b32 s28, s14, 12
	v_mov_b32_e32 v178, v72
	v_mov_b32_e32 v179, v1
	global_load_dwordx4 v[192:195], v[176:177], off
	global_load_dwordx4 v[196:199], v[176:177], off offset:64
	global_load_dwordx4 v[206:209], v[176:177], off offset:128
	v_lshl_add_u64 v[176:177], v[40:41], 0, s[28:29]
	v_lshl_add_u64 v[178:179], v[176:177], 0, v[178:179]
	v_lshl_add_u64 v[176:177], v[176:177], 0, v[0:1]
	global_load_dwordx4 v[222:225], v[178:179], off offset:144
	global_load_dwordx4 v[226:229], v[178:179], off offset:128
	global_load_dwordx4 v[210:213], v[176:177], off
	global_load_dwordx4 v[218:221], v[176:177], off offset:64
	s_waitcnt vmcnt(0)
	s_and_saveexec_b64 s[10:11], vcc
	s_cbranch_execz .LBB0_789
	v_mov_b32_e32 v6, v180
	v_mov_b32_e32 v7, v181
	v_mov_b32_e32 v8, v182
	v_mov_b32_e32 v9, v183
	v_lshlrev_b32_e32 v11, 16, v7
	v_lshlrev_b32_e32 v10, 16, v6
	v_and_b32_e32 v7, 0xffff0000, v7
	v_and_b32_e32 v6, 0xffff0000, v6
	v_pk_mul_f32 v[6:7], v[6:7], v[6:7]
	s_nop 0
	v_pk_fma_f32 v[6:7], v[10:11], v[10:11], v[6:7]
	v_lshlrev_b32_e32 v11, 16, v9
	v_lshlrev_b32_e32 v10, 16, v8
	v_and_b32_e32 v9, 0xffff0000, v9
	v_and_b32_e32 v8, 0xffff0000, v8
	v_pk_mul_f32 v[8:9], v[8:9], v[8:9]
	v_add_f32_e32 v2, v6, v7
	v_pk_fma_f32 v[8:9], v[10:11], v[10:11], v[8:9]
	s_nop 0
	v_add_f32_e32 v2, v8, v2
	v_add_f32_e32 v2, v9, v2
.LBB0_789:
	s_or_b64 exec, exec, s[10:11]
	s_ashr_i32 s15, s14, 31
	s_and_saveexec_b64 s[10:11], s[4:5]
	s_cbranch_execz .LBB0_786
	v_mov_b32_e32 v4, v184
	v_mov_b32_e32 v5, v185
	v_mov_b32_e32 v6, v186
	v_mov_b32_e32 v7, v187
	v_lshlrev_b32_e32 v9, 16, v5
	v_lshlrev_b32_e32 v8, 16, v4
	v_and_b32_e32 v5, 0xffff0000, v5
	v_and_b32_e32 v4, 0xffff0000, v4
	v_pk_mul_f32 v[4:5], v[4:5], v[4:5]
	s_nop 0
	v_pk_fma_f32 v[4:5], v[8:9], v[8:9], v[4:5]
	v_lshlrev_b32_e32 v9, 16, v7
	v_lshlrev_b32_e32 v8, 16, v6
	v_and_b32_e32 v7, 0xffff0000, v7
	v_and_b32_e32 v6, 0xffff0000, v6
	v_pk_mul_f32 v[6:7], v[6:7], v[6:7]
	v_add_f32_e32 v3, v4, v5
	v_pk_fma_f32 v[6:7], v[8:9], v[8:9], v[6:7]
	s_nop 0
	v_add_f32_e32 v3, v6, v3
	v_add_f32_e32 v3, v7, v3
	s_branch .LBB0_786
